# SSD chunk-state tiles: MFMA operands swapped so the accumulator holds the transposed tile, stored as 4 dword stores over contiguous 64-byte row segments (was dwordx4 to 16 rows)
# speedup vs baseline: 1.0560x; 1.0034x over previous
.LBB0_1402:
	s_or_b64 exec, exec, s[2:3]
	v_ashrrev_i32_e32 v38, 7, v10
	v_add_u32_e32 v46, s17, v38
	v_readlane_b32 s68, v254, 4
	v_ashrrev_i32_e32 v47, 31, v46
	v_readlane_b32 s80, v254, 16
	v_readlane_b32 s81, v254, 17
	s_waitcnt lgkmcnt(0)
	s_barrier
	v_and_b32_e32 v128, 15, v0
	v_bfe_u32 v129, v0, 4, 2
	v_mul_u32_u24_e32 v129, 0x7f0, v129
	v_mul_u32_u24_e32 v128, 0x1fc, v128
	v_sub_u32_e32 v128, v129, v128
	v_ashrrev_i32_e32 v129, 31, v128
	v_lshl_add_u64 v[2:3], v[46:47], 2, s[80:81]
	global_load_dword v57, v[2:3], off
	v_and_b32_e32 v2, 48, v11
	v_and_b32_e32 v53, 15, v10
	v_add_u32_e32 v52, 16, v2
	s_movk_i32 s2, 0x110
	v_mad_u32_u24 v30, v53, s2, v52
	ds_read_b128 v[22:25], v30 offset:4096
	v_bfe_u32 v54, v10, 6, 1
	v_lshl_or_b32 v45, v54, 5, v53
	v_mad_u32_u24 v39, v45, s2, v52
	ds_read_b128 v[6:9], v39 offset:21504
	ds_read_b128 v[18:21], v30 offset:4160
	ds_read_b128 v[14:17], v39 offset:21568
	ds_read_b128 v[26:29], v30 offset:4224
	s_waitcnt lgkmcnt(3)
	v_mfma_f32_16x16x32_bf16 v[2:5], v[22:25], v[6:9], 0
	v_lshrrev_b32_e32 v60, 4, v11
	ds_read_b128 v[10:13], v39 offset:21632
	ds_read_b128 v[30:33], v30 offset:4288
	s_movk_i32 s2, 0x1200
	s_waitcnt lgkmcnt(3)
	v_mfma_f32_16x16x32_bf16 v[34:37], v[18:21], v[14:17], v[2:5]
	v_mul_lo_u32 v55, v38, s2
	v_lshl_add_u32 v44, v55, 1, 16
	s_movk_i32 s2, 0xdd00
	ds_read_b128 v[2:5], v39 offset:21696
	v_lshlrev_b32_e32 v40, 2, v45
	s_waitcnt lgkmcnt(2)
	v_mfma_f32_16x16x32_bf16 v[34:37], v[26:29], v[10:13], v[34:37]
	v_mad_u64_u32 v[42:43], s[2:3], v38, s2, v[44:45]
	v_lshl_or_b32 v38, v38, 8, v40
	v_add_u32_e32 v43, 16, v38
	ds_read_b32 v40, v43
	s_waitcnt lgkmcnt(1)
	v_mfma_f32_16x16x32_bf16 v[36:39], v[30:33], v[2:5], v[34:37]
	v_lshlrev_b32_e32 v56, 2, v60
	v_cmp_ge_u32_e64 s[6:7], v45, v56
	v_lshl_add_u32 v61, v56, 2, v42
	v_mov_b32_e32 v35, 0
	v_mov_b32_e32 v34, 0
	v_readlane_b32 s69, v254, 5
	v_readlane_b32 s70, v254, 6
	v_readlane_b32 s71, v254, 7
	v_readlane_b32 s72, v254, 8
	v_readlane_b32 s73, v254, 9
	v_readlane_b32 s74, v254, 10
	v_readlane_b32 s75, v254, 11
	v_readlane_b32 s76, v254, 12
	v_readlane_b32 s77, v254, 13
	v_readlane_b32 s78, v254, 14
	v_readlane_b32 s79, v254, 15
	v_readlane_b32 s82, v254, 18
	v_readlane_b32 s83, v254, 19
	s_and_saveexec_b64 s[2:3], s[6:7]
	s_cbranch_execz .LBB0_1404
	ds_read_b32 v34, v61
	s_waitcnt lgkmcnt(0)
	v_sub_f32_e32 v34, v40, v34
	v_mul_f32_e32 v34, 0x3fb8aa3b, v34
	v_exp_f32_e32 v34, v34
	s_nop 0
	v_mul_f32_e32 v34, v36, v34

.LBB0_1490:
	s_or_b64 exec, exec, s[6:7]
	s_and_b64 s[0:1], s[0:1], exec
	v_readlane_b32 s0, v254, 61
	s_cselect_b32 s92, s14, s15
	s_cselect_b32 s2, s0, s89
	v_readlane_b32 s0, v254, 60
	s_cselect_b32 s3, s0, s88
	s_lshl_b64 s[0:1], s[92:93], 18
	s_add_u32 s0, s3, s0
	s_addc_u32 s1, s2, s1
	v_lshlrev_b64 v[2:3], 15, v[46:47]
	v_lshl_add_u64 v[2:3], s[0:1], 0, v[2:3]
	v_readlane_b32 s0, v255, 1
	v_lshl_or_b32 v60, v54, 6, v53
	s_movk_i32 s2, 0x90
	v_lshl_add_u32 v4, v55, 1, s0
	v_lshlrev_b32_e32 v5, 1, v58
	v_mad_u32_u24 v10, v60, s2, v52
	v_add3_u32 v50, v4, v5, v59
	ds_read_b128 v[26:29], v10 offset:38912
	ds_read_b128 v[30:33], v50
	v_lshlrev_b32_e32 v78, 2, v56
	v_lshl_add_u64 v[2:3], v[2:3], 0, v[78:79]
	v_lshlrev_b32_e32 v78, 8, v54
	v_lshl_add_u64 v[40:41], v[2:3], 0, v[78:79]
	ds_read_b128 v[42:45], v10 offset:38976
	ds_read_b128 v[2:5], v50 offset:64
	s_waitcnt lgkmcnt(2)
	v_mfma_f32_16x16x32_bf16 v[6:9], v[30:33], v[26:29], 0
	ds_read_b128 v[18:21], v50 offset:2304
	ds_read_b128 v[10:13], v50 offset:2368
	v_lshlrev_b32_e32 v78, 9, v53
	s_waitcnt lgkmcnt(2)
	v_mfma_f32_16x16x32_bf16 v[6:9], v[2:5], v[42:45], v[6:9]
	v_lshl_add_u64 v[34:35], v[40:41], 0, v[78:79]
	ds_read_b128 v[22:25], v50 offset:4608
	v_or_b32_e32 v38, 0x2000, v78
	v_mov_b32_e32 v39, v79
	v_lshl_add_u64 v[14:15], v[40:41], 0, v[38:39]
	s_nop 2
	v_lshl_add_u64 v[130:131], v[34:35], 0, v[128:129]
	global_store_dword v[130:131], v6, off
	global_store_dword v[130:131], v7, off offset:512
	global_store_dword v[130:131], v8, off offset:1024
	global_store_dword v[130:131], v9, off offset:1536
	v_or_b32_e32 v36, 0x4000, v78
	v_mov_b32_e32 v37, v79
	s_waitcnt lgkmcnt(2)
	v_mfma_f32_16x16x32_bf16 v[6:9], v[18:21], v[26:29], 0
	v_lshl_add_u64 v[46:47], v[40:41], 0, v[36:37]
	v_or_b32_e32 v78, 0x6000, v78
	s_mov_b64 s[0:1], 0x80
	s_waitcnt lgkmcnt(1)
	v_mfma_f32_16x16x32_bf16 v[6:9], v[10:13], v[42:45], v[6:9]
	s_nop 7
	v_lshl_add_u64 v[130:131], v[14:15], 0, v[128:129]
	global_store_dword v[130:131], v6, off
	global_store_dword v[130:131], v7, off offset:512
	global_store_dword v[130:131], v8, off offset:1024
	global_store_dword v[130:131], v9, off offset:1536
	ds_read_b128 v[6:9], v50 offset:4672
	s_waitcnt lgkmcnt(1)
	v_mfma_f32_16x16x32_bf16 v[14:17], v[22:25], v[26:29], 0
	s_waitcnt lgkmcnt(0)
	v_mfma_f32_16x16x32_bf16 v[14:17], v[6:9], v[42:45], v[14:17]
	s_nop 7
	v_lshl_add_u64 v[130:131], v[46:47], 0, v[128:129]
	global_store_dword v[130:131], v14, off
	global_store_dword v[130:131], v15, off offset:512
	global_store_dword v[130:131], v16, off offset:1024
	global_store_dword v[130:131], v17, off offset:1536
	ds_read_b128 v[14:17], v50 offset:6912
	s_waitcnt lgkmcnt(0)
	v_mfma_f32_16x16x32_bf16 v[46:49], v[14:17], v[26:29], 0
	ds_read_b128 v[26:29], v50 offset:6976
	v_lshl_add_u64 v[50:51], v[40:41], 0, 64
	v_lshl_add_u64 v[58:59], v[50:51], 0, v[38:39]
	s_waitcnt lgkmcnt(0)
	v_mfma_f32_16x16x32_bf16 v[42:45], v[26:29], v[42:45], v[46:49]
	s_nop 2
	v_lshl_add_u64 v[46:47], v[40:41], 0, v[78:79]
	s_nop 3
	v_lshl_add_u64 v[130:131], v[46:47], 0, v[128:129]
	global_store_dword v[130:131], v42, off
	global_store_dword v[130:131], v43, off offset:512
	global_store_dword v[130:131], v44, off offset:1024
	global_store_dword v[130:131], v45, off offset:1536
	s_nop 1
	v_or_b32_e32 v42, 16, v60
	v_mad_u32_u24 v53, v42, s2, v52
	ds_read_b128 v[42:45], v53 offset:38912
	s_waitcnt vmcnt(4)
	ds_read_b128 v[54:57], v53 offset:38976
	s_waitcnt lgkmcnt(1)
	v_mfma_f32_16x16x32_bf16 v[46:49], v[30:33], v[42:45], 0
	s_waitcnt lgkmcnt(0)
	v_mfma_f32_16x16x32_bf16 v[46:49], v[2:5], v[54:57], v[46:49]
	s_nop 7
	v_lshl_add_u64 v[130:131], v[34:35], 0, v[128:129]
	global_store_dword v[130:131], v46, off offset:64
	global_store_dword v[130:131], v47, off offset:576
	global_store_dword v[130:131], v48, off offset:1088
	global_store_dword v[130:131], v49, off offset:1600
	s_nop 1
	v_mfma_f32_16x16x32_bf16 v[46:49], v[18:21], v[42:45], 0
	v_mfma_f32_16x16x32_bf16 v[46:49], v[10:13], v[54:57], v[46:49]
	s_nop 7
	v_lshl_add_u64 v[130:131], v[58:59], 0, v[128:129]
	global_store_dword v[130:131], v46, off
	global_store_dword v[130:131], v47, off offset:512
	global_store_dword v[130:131], v48, off offset:1024
	global_store_dword v[130:131], v49, off offset:1536
	v_lshl_add_u64 v[58:59], v[50:51], 0, v[36:37]
	s_nop 0
	v_mfma_f32_16x16x32_bf16 v[46:49], v[22:25], v[42:45], 0
	v_mfma_f32_16x16x32_bf16 v[42:45], v[14:17], v[42:45], 0
	v_mfma_f32_16x16x32_bf16 v[46:49], v[6:9], v[54:57], v[46:49]
	v_mfma_f32_16x16x32_bf16 v[42:45], v[26:29], v[54:57], v[42:45]
	s_nop 6
	v_lshl_add_u64 v[130:131], v[58:59], 0, v[128:129]
	global_store_dword v[130:131], v46, off
	global_store_dword v[130:131], v47, off offset:512
	global_store_dword v[130:131], v48, off offset:1024
	global_store_dword v[130:131], v49, off offset:1536
	s_nop 1
	v_lshl_add_u64 v[46:47], v[50:51], 0, v[78:79]
	v_lshl_add_u64 v[130:131], v[46:47], 0, v[128:129]
	global_store_dword v[130:131], v42, off
	global_store_dword v[130:131], v43, off offset:512
	global_store_dword v[130:131], v44, off offset:1024
	global_store_dword v[130:131], v45, off offset:1536
	v_lshl_add_u64 v[50:51], v[40:41], 0, s[0:1]
	v_lshl_add_u64 v[58:59], v[50:51], 0, v[38:39]
	v_or_b32_e32 v42, 32, v60
	v_mad_u32_u24 v53, v42, s2, v52
	ds_read_b128 v[42:45], v53 offset:38912
	ds_read_b128 v[54:57], v53 offset:38976
	s_waitcnt lgkmcnt(1)
	v_mfma_f32_16x16x32_bf16 v[46:49], v[30:33], v[42:45], 0
	s_mov_b64 s[0:1], 0xc0
	s_waitcnt lgkmcnt(0)
	v_mfma_f32_16x16x32_bf16 v[46:49], v[2:5], v[54:57], v[46:49]
	s_nop 7
	v_lshl_add_u64 v[130:131], v[34:35], 0, v[128:129]
	global_store_dword v[130:131], v46, off offset:128
	global_store_dword v[130:131], v47, off offset:640
	global_store_dword v[130:131], v48, off offset:1152
	global_store_dword v[130:131], v49, off offset:1664
	s_nop 1
	v_mfma_f32_16x16x32_bf16 v[46:49], v[18:21], v[42:45], 0
	v_mfma_f32_16x16x32_bf16 v[46:49], v[10:13], v[54:57], v[46:49]
	s_nop 7
	v_lshl_add_u64 v[130:131], v[58:59], 0, v[128:129]
	global_store_dword v[130:131], v46, off
	global_store_dword v[130:131], v47, off offset:512
	global_store_dword v[130:131], v48, off offset:1024
	global_store_dword v[130:131], v49, off offset:1536
	v_lshl_add_u64 v[58:59], v[50:51], 0, v[36:37]
	s_nop 0
	v_mfma_f32_16x16x32_bf16 v[46:49], v[22:25], v[42:45], 0
	v_mfma_f32_16x16x32_bf16 v[42:45], v[14:17], v[42:45], 0
	v_mfma_f32_16x16x32_bf16 v[46:49], v[6:9], v[54:57], v[46:49]
	v_mfma_f32_16x16x32_bf16 v[42:45], v[26:29], v[54:57], v[42:45]
	s_nop 6
	v_lshl_add_u64 v[130:131], v[58:59], 0, v[128:129]
	global_store_dword v[130:131], v46, off
	global_store_dword v[130:131], v47, off offset:512
	global_store_dword v[130:131], v48, off offset:1024
	global_store_dword v[130:131], v49, off offset:1536
	s_nop 1
	v_lshl_add_u64 v[46:47], v[50:51], 0, v[78:79]
	v_lshl_add_u64 v[130:131], v[46:47], 0, v[128:129]
	global_store_dword v[130:131], v42, off
	global_store_dword v[130:131], v43, off offset:512
	global_store_dword v[130:131], v44, off offset:1024
	global_store_dword v[130:131], v45, off offset:1536
	v_lshl_add_u64 v[48:49], v[40:41], 0, s[0:1]
	s_nop 0
	v_or_b32_e32 v42, 48, v60
	v_mad_u32_u24 v44, v42, s2, v52
	ds_read_b128 v[40:43], v44 offset:38912
	ds_read_b128 v[44:47], v44 offset:38976
	s_waitcnt lgkmcnt(1)
	v_mfma_f32_16x16x32_bf16 v[30:33], v[30:33], v[40:43], 0
	s_waitcnt lgkmcnt(0)
	v_mfma_f32_16x16x32_bf16 v[2:5], v[2:5], v[44:47], v[30:33]
	s_nop 7
	v_lshl_add_u64 v[130:131], v[34:35], 0, v[128:129]
	global_store_dword v[130:131], v2, off offset:192
	global_store_dword v[130:131], v3, off offset:704
	global_store_dword v[130:131], v4, off offset:1216
	global_store_dword v[130:131], v5, off offset:1728
	s_nop 1
	v_mfma_f32_16x16x32_bf16 v[2:5], v[18:21], v[40:43], 0
	v_mfma_f32_16x16x32_bf16 v[2:5], v[10:13], v[44:47], v[2:5]
	v_lshl_add_u64 v[10:11], v[48:49], 0, v[38:39]
	s_nop 6
	v_lshl_add_u64 v[130:131], v[10:11], 0, v[128:129]
	global_store_dword v[130:131], v2, off
	global_store_dword v[130:131], v3, off offset:512
	global_store_dword v[130:131], v4, off offset:1024
	global_store_dword v[130:131], v5, off offset:1536
	s_nop 1
	v_mfma_f32_16x16x32_bf16 v[2:5], v[22:25], v[40:43], 0
	v_mfma_f32_16x16x32_bf16 v[2:5], v[6:9], v[44:47], v[2:5]
	v_lshl_add_u64 v[6:7], v[48:49], 0, v[36:37]
	s_nop 6
	v_lshl_add_u64 v[130:131], v[6:7], 0, v[128:129]
	global_store_dword v[130:131], v2, off
	global_store_dword v[130:131], v3, off offset:512
	global_store_dword v[130:131], v4, off offset:1024
	global_store_dword v[130:131], v5, off offset:1536
	v_lshl_add_u64 v[6:7], v[48:49], 0, v[78:79]
	s_nop 0
	v_mfma_f32_16x16x32_bf16 v[2:5], v[14:17], v[40:43], 0
	v_mfma_f32_16x16x32_bf16 v[2:5], v[26:29], v[44:47], v[2:5]
	s_nop 7
	v_lshl_add_u64 v[130:131], v[6:7], 0, v[128:129]
	global_store_dword v[130:131], v2, off
	global_store_dword v[130:131], v3, off offset:512
	global_store_dword v[130:131], v4, off offset:1024
	global_store_dword v[130:131], v5, off offset:1536
	s_barrier
	s_cbranch_execz .LBB0_1108
	s_branch .LBB0_1799
